# attention QK: all 12 K-fragment LDS reads issued up front into VGPR+AGPR quads, MFMAs behind counted lgkmcnt
# speedup vs baseline: 1.0379x; 1.0379x over previous
; #define LAS __attribute__((address_space(3)))
; DI void phase_attn(const Params& p, int l, LAS char* lds) {
;     ...
;             LAS char* st = lds + (kt & 1) * 20480;
;             f32x16 s0, s1;
; #pragma unroll
;             for (int r = 0; r < 16; ++r) { s0[r] = 0.f; s1[r] = 0.f; }
; #pragma unroll
;             for (int s = 0; s < 6; ++s) {
;                 const int pos = ((2 * s + hh) ^ ksw) << 4;
;                 const bf16x8 k0 = *(LAS bf16x8*)(st + qi * 192 + pos);
;                 const bf16x8 k1 = *(LAS bf16x8*)(st + (qi + 32) * 192 + pos);
;                 s0 = __builtin_amdgcn_mfma_f32_32x32x16_bf16(k0, qf[s], s0, 0, 0, 0);
;                 s1 = __builtin_amdgcn_mfma_f32_32x32x16_bf16(k1, qf[s], s1, 0, 0, 0);
;             }
.LBB0_288:
	s_bitcmp1_b32 s4, 0
	s_cselect_b32 s34, 0x5000, 0
	s_cbranch_scc1 .Lqk_s1
	ds_read_b128 v[34:37], v188 offset:0
	ds_read_b128 v[50:53], v188 offset:6144
	ds_read_b128 v[184:187], v189 offset:0
	ds_read_b128 a[0:3], v189 offset:6144
	ds_read_b128 v[204:207], v190 offset:0
	ds_read_b128 a[4:7], v190 offset:6144
	ds_read_b128 v[220:223], v191 offset:0
	ds_read_b128 a[8:11], v191 offset:6144
	ds_read_b128 v[224:227], v192 offset:0
	ds_read_b128 a[12:15], v192 offset:6144
	ds_read_b128 a[16:19], v193 offset:0
	ds_read_b128 a[20:23], v193 offset:6144
	s_add_i32 s4, s23, 63
	v_cmp_gt_i32_e32 vcc, s4, v123
	s_waitcnt lgkmcnt(10)
	v_mfma_f32_32x32x16_bf16 v[34:49], v[34:37], v[66:69], 0
	v_mfma_f32_32x32x16_bf16 v[50:65], v[50:53], v[66:69], 0
	s_waitcnt lgkmcnt(8)
	v_mfma_f32_32x32x16_bf16 v[34:49], v[184:187], v[70:73], v[34:49]
	v_mfma_f32_32x32x16_bf16 v[50:65], a[0:3], v[70:73], v[50:65]
	s_waitcnt lgkmcnt(6)
	v_mfma_f32_32x32x16_bf16 v[34:49], v[204:207], v[74:77], v[34:49]
	v_mfma_f32_32x32x16_bf16 v[50:65], a[4:7], v[74:77], v[50:65]
	s_waitcnt lgkmcnt(4)
	v_mfma_f32_32x32x16_bf16 v[34:49], v[220:223], v[78:81], v[34:49]
	v_mfma_f32_32x32x16_bf16 v[50:65], a[8:11], v[78:81], v[50:65]
	s_waitcnt lgkmcnt(2)
	v_mfma_f32_32x32x16_bf16 v[34:49], v[224:227], v[82:85], v[34:49]
	v_mfma_f32_32x32x16_bf16 v[50:65], a[12:15], v[82:85], v[50:65]
	s_waitcnt lgkmcnt(0)
	v_mfma_f32_32x32x16_bf16 v[34:49], a[16:19], v[86:89], v[34:49]
	v_mfma_f32_32x32x16_bf16 v[50:65], a[20:23], v[86:89], v[50:65]
	s_nop 1
	s_branch .Lqk_done
.Lqk_s1:
	ds_read_b128 v[34:37], v188 offset:20480
	ds_read_b128 v[50:53], v188 offset:26624
	ds_read_b128 v[184:187], v189 offset:20480
	ds_read_b128 a[0:3], v189 offset:26624
	ds_read_b128 v[204:207], v190 offset:20480
	ds_read_b128 a[4:7], v190 offset:26624
	ds_read_b128 v[220:223], v191 offset:20480
	ds_read_b128 a[8:11], v191 offset:26624
	ds_read_b128 v[224:227], v192 offset:20480
	ds_read_b128 a[12:15], v192 offset:26624
	ds_read_b128 a[16:19], v193 offset:20480
	ds_read_b128 a[20:23], v193 offset:26624
	s_add_i32 s4, s23, 63
	v_cmp_gt_i32_e32 vcc, s4, v123
	s_waitcnt lgkmcnt(10)
	v_mfma_f32_32x32x16_bf16 v[34:49], v[34:37], v[66:69], 0
	v_mfma_f32_32x32x16_bf16 v[50:65], v[50:53], v[66:69], 0
	s_waitcnt lgkmcnt(8)
	v_mfma_f32_32x32x16_bf16 v[34:49], v[184:187], v[70:73], v[34:49]
	v_mfma_f32_32x32x16_bf16 v[50:65], a[0:3], v[70:73], v[50:65]
	s_waitcnt lgkmcnt(6)
	v_mfma_f32_32x32x16_bf16 v[34:49], v[204:207], v[74:77], v[34:49]
	v_mfma_f32_32x32x16_bf16 v[50:65], a[4:7], v[74:77], v[50:65]
	s_waitcnt lgkmcnt(4)
	v_mfma_f32_32x32x16_bf16 v[34:49], v[220:223], v[78:81], v[34:49]
	v_mfma_f32_32x32x16_bf16 v[50:65], a[8:11], v[78:81], v[50:65]
	s_waitcnt lgkmcnt(2)
	v_mfma_f32_32x32x16_bf16 v[34:49], v[224:227], v[82:85], v[34:49]
	v_mfma_f32_32x32x16_bf16 v[50:65], a[12:15], v[82:85], v[50:65]
	s_waitcnt lgkmcnt(0)
	v_mfma_f32_32x32x16_bf16 v[34:49], a[16:19], v[86:89], v[34:49]
	v_mfma_f32_32x32x16_bf16 v[50:65], a[20:23], v[86:89], v[50:65]
	s_nop 1

; __global__ void __launch_bounds__(256, 2) mega(Params p) {
;     __shared__ __attribute__((aligned(16))) char smem[65536];
	.amdhsa_kernel _Z4mega6Params
		.amdhsa_group_segment_fixed_size 65536
		.amdhsa_private_segment_fixed_size 0
		.amdhsa_kernarg_size 456
		.amdhsa_user_sgpr_count 2
		.amdhsa_user_sgpr_dispatch_ptr 0
		.amdhsa_user_sgpr_queue_ptr 0
		.amdhsa_user_sgpr_kernarg_segment_ptr 1
		.amdhsa_user_sgpr_dispatch_id 0
		.amdhsa_user_sgpr_kernarg_preload_length 0
		.amdhsa_user_sgpr_kernarg_preload_offset 0
		.amdhsa_user_sgpr_private_segment_size 0
		.amdhsa_uses_dynamic_stack 0
		.amdhsa_enable_private_segment 0
		.amdhsa_system_sgpr_workgroup_id_x 1
		.amdhsa_system_sgpr_workgroup_id_y 0
		.amdhsa_system_sgpr_workgroup_id_z 0
		.amdhsa_system_sgpr_workgroup_info 0
		.amdhsa_system_vgpr_workitem_id 2
		.amdhsa_next_free_vgpr 256
		.amdhsa_next_free_sgpr 102
		.amdhsa_accum_offset 232
		.amdhsa_reserve_vcc 1
		.amdhsa_float_round_mode_32 0
		.amdhsa_float_round_mode_16_64 0
		.amdhsa_float_denorm_mode_32 3
		.amdhsa_float_denorm_mode_16_64 3
		.amdhsa_dx10_clamp 1
		.amdhsa_ieee_mode 1
		.amdhsa_fp16_overflow 0
		.amdhsa_tg_split 0
		.amdhsa_exception_fp_ieee_invalid_op 0
		.amdhsa_exception_fp_denorm_src 0
		.amdhsa_exception_fp_ieee_div_zero 0
		.amdhsa_exception_fp_ieee_overflow 0
		.amdhsa_exception_fp_ieee_underflow 0
		.amdhsa_exception_fp_ieee_inexact 0
		.amdhsa_exception_int_div_zero 0
	.end_amdhsa_kernel

; __global__ void __launch_bounds__(256, 2) mega(Params p) {
;     __shared__ __attribute__((aligned(16))) char smem[65536];
amdhsa.kernels:
  - .agpr_count:     24
    .args:
      - .offset:         0
        .size:           200
        .value_kind:     by_value
      - .offset:         200
        .size:           4
        .value_kind:     hidden_block_count_x
      - .offset:         204
        .size:           4
        .value_kind:     hidden_block_count_y
      - .offset:         208
        .size:           4
        .value_kind:     hidden_block_count_z
      - .offset:         212
        .size:           2
        .value_kind:     hidden_group_size_x
      - .offset:         214
        .size:           2
        .value_kind:     hidden_group_size_y
      - .offset:         216
        .size:           2
        .value_kind:     hidden_group_size_z
      - .offset:         218
        .size:           2
        .value_kind:     hidden_remainder_x
      - .offset:         220
        .size:           2
        .value_kind:     hidden_remainder_y
      - .offset:         222
        .size:           2
        .value_kind:     hidden_remainder_z
      - .offset:         240
        .size:           8
        .value_kind:     hidden_global_offset_x
      - .offset:         248
        .size:           8
        .value_kind:     hidden_global_offset_y
      - .offset:         256
        .size:           8
        .value_kind:     hidden_global_offset_z
      - .offset:         264
        .size:           2
        .value_kind:     hidden_grid_dims
      - .offset:         288
        .size:           8
        .value_kind:     hidden_multigrid_sync_arg
    .group_segment_fixed_size: 65536
    .kernarg_segment_align: 8
    .kernarg_segment_size: 456
    .language:       OpenCL C
    .language_version:
      - 2
      - 0
    .max_flat_workgroup_size: 256
    .name:           _Z4mega6Params
    .private_segment_fixed_size: 0
    .sgpr_count:     108
    .sgpr_spill_count: 226
    .symbol:         _Z4mega6Params.kd
    .uniform_work_group_size: 1
    .uses_dynamic_stack: false
    .vgpr_count:     256
    .vgpr_spill_count: 0
    .wavefront_size: 64
